# P5: touch the wave's next row (x + yh lines) into L2 once the current row's loads have landed
# speedup vs baseline: 1.0013x; 1.0013x over previous
; #define GAS __attribute__((address_space(1)))
; __device__ __forceinline__ float h_lo(unsigned w) { return (float)__builtin_bit_cast(_Float16, (unsigned short)(w & 0xffffu)); }
; __device__ __forceinline__ float h_hi(unsigned w) { return (float)__builtin_bit_cast(_Float16, (unsigned short)(w >> 16)); }
; template <bool SAMPLE, bool PRE = false> __device__ __forceinline__ void p5_row(Frame& F, int m, float* dst, const f32x4* xpre = nullptr) {
;     f32x4 v[16];
;     const GAS f32x4* x8 = (const GAS f32x4*)((SAMPLE ? F.in[2] + (size_t)(m - MP) * DM : F.in[0] + (size_t)m * DM)) + 2 * F.lane;
;     if (!SAMPLE) {
;         const GAS u32x4* yr = (const GAS u32x4*)(F.ws + WS_YH + (size_t)m * DM * 2) + F.lane;
;         u32x4 w[8];
; #pragma unroll
;         for (int j = 0; j < 8; ++j) { w[j] = yr[64 * j]; if constexpr (PRE) { v[2 * j] = xpre[2 * j]; v[2 * j + 1] = xpre[2 * j + 1]; } else { v[2 * j] = x8[128 * j]; v[2 * j + 1] = x8[128 * j + 1]; } }
; #pragma unroll
;         for (int j = 0; j < 8; ++j) { v[2 * j] += (f32x4){h_lo(w[j].x), h_hi(w[j].x), h_lo(w[j].y), h_hi(w[j].y)}; v[2 * j + 1] += (f32x4){h_lo(w[j].z), h_hi(w[j].z), h_lo(w[j].w), h_hi(w[j].w)}; }
.LBB0_842:
	v_lshl_add_u64 v[96:97], s[8:9], 0, v[130:131]
	global_load_dwordx4 v[12:15], v[94:95], off
	global_load_dwordx4 v[8:11], v[94:95], off offset:1024
	global_load_dwordx4 v[0:3], v[94:95], off offset:2048
	global_load_dwordx4 v[4:7], v[94:95], off offset:3072
	v_add_co_u32_e32 v136, vcc, 0x1000, v96
	v_lshl_add_u64 v[132:133], v[96:97], 0, s[4:5]
	s_nop 0
	v_addc_co_u32_e32 v137, vcc, 0, v97, vcc
	v_add_co_u32_e32 v156, vcc, 0x1000, v94
	v_lshl_add_u64 v[140:141], v[96:97], 0, s[12:13]
	s_nop 0
	v_addc_co_u32_e32 v157, vcc, 0, v95, vcc
	global_load_dwordx4 v[68:71], v[80:81], off offset:16
	global_load_dwordx4 v[76:79], v[80:81], off
	global_load_dwordx4 v[60:63], v[80:81], off offset:2064
	global_load_dwordx4 v[72:75], v[80:81], off offset:2048
	global_load_dwordx4 v[52:55], v[82:83], off offset:16
	global_load_dwordx4 v[64:67], v[82:83], off
	global_load_dwordx4 v[44:47], v[84:85], off offset:16
	global_load_dwordx4 v[56:59], v[84:85], off
	global_load_dwordx4 v[36:39], v[86:87], off offset:16
	global_load_dwordx4 v[48:51], v[86:87], off
	global_load_dwordx4 v[28:31], v[88:89], off offset:16
	global_load_dwordx4 v[40:43], v[88:89], off
	global_load_dwordx4 v[20:23], v[90:91], off offset:16
	global_load_dwordx4 v[32:35], v[90:91], off
	global_load_dwordx4 v[16:19], v[92:93], off offset:16
	global_load_dwordx4 v[24:27], v[92:93], off
	global_load_dwordx4 v[110:113], v[96:97], off offset:16
	global_load_dwordx4 v[114:117], v[96:97], off
	global_load_dwordx4 v[118:121], v[96:97], off offset:2064
	global_load_dwordx4 v[122:125], v[96:97], off offset:2048
	global_load_dwordx4 v[126:129], v[136:137], off
	s_nop 0
	global_load_dwordx4 v[132:135], v[132:133], off offset:16
	s_nop 0
	global_load_dwordx4 v[136:139], v[136:137], off offset:2048
	s_nop 0
	global_load_dwordx4 v[140:143], v[140:141], off offset:16
	s_nop 0
	global_load_dwordx4 v[144:147], v[156:157], off
	global_load_dwordx4 v[148:151], v[156:157], off offset:1024
	global_load_dwordx4 v[152:155], v[156:157], off offset:2048
	v_add_co_u32_e32 v168, vcc, 0x2000, v96
	global_load_dwordx4 v[156:159], v[156:157], off offset:3072
	v_lshl_add_u64 v[164:165], v[96:97], 0, s[14:15]
	v_lshl_add_u64 v[172:173], v[96:97], 0, s[16:17]
	v_addc_co_u32_e32 v169, vcc, 0, v97, vcc
	global_load_dwordx4 v[160:163], v[168:169], off
	s_nop 0
	global_load_dwordx4 v[164:167], v[164:165], off offset:16
	s_nop 0
	global_load_dwordx4 v[168:171], v[168:169], off offset:2048
	s_nop 0
	global_load_dwordx4 v[172:175], v[172:173], off offset:16
	v_lshl_add_u64 v[180:181], v[96:97], 0, s[18:19]
	v_lshl_add_u64 v[188:189], v[96:97], 0, s[20:21]
	v_add_co_u32_e32 v96, vcc, 0x3000, v96
	v_lshl_add_u64 v[98:99], s[6:7], 0, v[130:131]
	s_nop 0
	v_addc_co_u32_e32 v97, vcc, 0, v97, vcc
	global_load_dwordx4 v[176:179], v[96:97], off
	s_nop 0
	global_load_dwordx4 v[180:183], v[180:181], off offset:16
	s_nop 0
	global_load_dwordx4 v[184:187], v[96:97], off offset:2048
	s_nop 0
	global_load_dwordx4 v[188:191], v[188:189], off offset:16
	v_add_co_u32_e64 v104, s[0:1], s23, v98
	v_mov_b32_e32 v109, 0
	s_nop 0
	v_addc_co_u32_e64 v105, s[0:1], 0, v99, s[0:1]
	v_add_co_u32_e64 v102, s[0:1], s24, v98
	v_mov_b32_e32 v208, 0
	s_nop 0
	v_addc_co_u32_e64 v103, s[0:1], 0, v99, s[0:1]
	v_add_co_u32_e64 v100, s[0:1], s25, v98
	s_add_i32 s22, s22, s28
	s_nop 0
	v_addc_co_u32_e64 v101, s[0:1], 0, v99, s[0:1]
	s_add_u32 s6, s6, s10
	s_addc_u32 s7, s7, s11
	s_add_u32 s8, s8, s10
	s_addc_u32 s9, s9, s11
	v_lshl_add_u64 v[94:95], v[94:95], 0, s[2:3]
	s_cmp_lt_i32 s22, s99
	s_waitcnt vmcnt(39)
	v_cvt_f32_f16_sdwa v97, v12 dst_sel:DWORD dst_unused:UNUSED_PAD src0_sel:WORD_1
	v_cvt_f32_f16_e32 v96, v12
	v_cvt_f32_f16_sdwa v193, v13 dst_sel:DWORD dst_unused:UNUSED_PAD src0_sel:WORD_1
	v_cvt_f32_f16_e32 v192, v13
	v_cvt_f32_f16_sdwa v13, v14 dst_sel:DWORD dst_unused:UNUSED_PAD src0_sel:WORD_1
	v_cvt_f32_f16_e32 v12, v14
	v_cvt_f32_f16_sdwa v195, v15 dst_sel:DWORD dst_unused:UNUSED_PAD src0_sel:WORD_1
	v_cvt_f32_f16_e32 v194, v15
	s_waitcnt vmcnt(38)
	v_cvt_f32_f16_sdwa v15, v8 dst_sel:DWORD dst_unused:UNUSED_PAD src0_sel:WORD_1
	v_cvt_f32_f16_e32 v14, v8
	v_cvt_f32_f16_sdwa v197, v9 dst_sel:DWORD dst_unused:UNUSED_PAD src0_sel:WORD_1
	v_cvt_f32_f16_e32 v196, v9
	v_cvt_f32_f16_sdwa v9, v10 dst_sel:DWORD dst_unused:UNUSED_PAD src0_sel:WORD_1
	v_cvt_f32_f16_e32 v8, v10
	v_cvt_f32_f16_sdwa v199, v11 dst_sel:DWORD dst_unused:UNUSED_PAD src0_sel:WORD_1
	v_cvt_f32_f16_e32 v198, v11
	s_waitcnt vmcnt(37)
	v_cvt_f32_f16_sdwa v11, v0 dst_sel:DWORD dst_unused:UNUSED_PAD src0_sel:WORD_1
	v_cvt_f32_f16_e32 v10, v0
	v_cvt_f32_f16_sdwa v201, v1 dst_sel:DWORD dst_unused:UNUSED_PAD src0_sel:WORD_1
	v_cvt_f32_f16_e32 v200, v1
	v_cvt_f32_f16_sdwa v1, v2 dst_sel:DWORD dst_unused:UNUSED_PAD src0_sel:WORD_1
	v_cvt_f32_f16_e32 v0, v2
	v_cvt_f32_f16_sdwa v203, v3 dst_sel:DWORD dst_unused:UNUSED_PAD src0_sel:WORD_1
	v_cvt_f32_f16_e32 v202, v3
	s_waitcnt vmcnt(36)
	v_cvt_f32_f16_sdwa v3, v4 dst_sel:DWORD dst_unused:UNUSED_PAD src0_sel:WORD_1
	v_cvt_f32_f16_e32 v2, v4
	v_cvt_f32_f16_sdwa v205, v5 dst_sel:DWORD dst_unused:UNUSED_PAD src0_sel:WORD_1
	v_cvt_f32_f16_e32 v204, v5
	v_cvt_f32_f16_sdwa v5, v6 dst_sel:DWORD dst_unused:UNUSED_PAD src0_sel:WORD_1
	v_cvt_f32_f16_e32 v4, v6
	v_cvt_f32_f16_sdwa v207, v7 dst_sel:DWORD dst_unused:UNUSED_PAD src0_sel:WORD_1
	v_cvt_f32_f16_e32 v206, v7
	s_waitcnt vmcnt(18)
	v_pk_add_f32 v[6:7], v[116:117], v[192:193]
	v_pk_add_f32 v[96:97], v[114:115], v[96:97]
	v_pk_add_f32 v[112:113], v[112:113], v[194:195]
	v_pk_add_f32 v[12:13], v[110:111], v[12:13]
	s_waitcnt vmcnt(16)
; #define GAS __attribute__((address_space(1)))
; __device__ __forceinline__ float h_lo(unsigned w) { return (float)__builtin_bit_cast(_Float16, (unsigned short)(w & 0xffffu)); }
; __device__ __forceinline__ float h_hi(unsigned w) { return (float)__builtin_bit_cast(_Float16, (unsigned short)(w >> 16)); }
; template <bool SAMPLE, bool PRE = false> __device__ __forceinline__ void p5_row(Frame& F, int m, float* dst, const f32x4* xpre = nullptr) {
;     ...
;         for (int j = 0; j < 8; ++j) { w[j] = yr[64 * j]; if constexpr (PRE) { v[2 * j] = xpre[2 * j]; v[2 * j + 1] = xpre[2 * j + 1]; } else { v[2 * j] = x8[128 * j]; v[2 * j + 1] = x8[128 * j + 1]; } }
; #pragma unroll
;         for (int j = 0; j < 8; ++j) { v[2 * j] += (f32x4){h_lo(w[j].x), h_hi(w[j].x), h_lo(w[j].y), h_hi(w[j].y)}; v[2 * j + 1] += (f32x4){h_lo(w[j].z), h_hi(w[j].z), h_lo(w[j].w), h_hi(w[j].w)}; }
;     } else {
; #pragma unroll
;         for (int j = 0; j < 8; ++j) { v[2 * j] = x8[128 * j]; v[2 * j + 1] = x8[128 * j + 1]; }
; #pragma unroll 2
;         for (int p = 0; p < 8; ++p) { const GAS u32x4* pr = (const GAS u32x4*)(F.ws + WS_SLAB + ((size_t)p * MS + (m - MP)) * DM * 2) + F.lane;
;             u32x4 w[8];
; #pragma unroll
;             for (int j = 0; j < 8; ++j) w[j] = pr[64 * j];
; #pragma unroll
;             for (int j = 0; j < 8; ++j) { v[2 * j] += (f32x4){h_lo(w[j].x), h_hi(w[j].x), h_lo(w[j].y), h_hi(w[j].y)}; v[2 * j + 1] += (f32x4){h_lo(w[j].z), h_hi(w[j].z), h_lo(w[j].w), h_hi(w[j].w)}; } }
;     }
;     float s = 0.f;
; #pragma unroll
;     for (int j = 0; j < 16; ++j) s += (v[j].x * v[j].x + v[j].y * v[j].y) + (v[j].z * v[j].z + v[j].w * v[j].w);
;     const float rstd = 1.0f / sqrtf(wave_sum(s) * (1.0f / DM) + EPS);
	v_pk_add_f32 v[110:111], v[124:125], v[196:197]
	v_pk_add_f32 v[14:15], v[122:123], v[14:15]
	v_pk_add_f32 v[114:115], v[120:121], v[198:199]
	v_pk_add_f32 v[8:9], v[118:119], v[8:9]
	s_waitcnt vmcnt(15)
	v_pk_add_f32 v[116:117], v[128:129], v[200:201]
	v_pk_add_f32 v[10:11], v[126:127], v[10:11]
	s_waitcnt vmcnt(14)
	v_pk_add_f32 v[118:119], v[134:135], v[202:203]
	v_pk_add_f32 v[0:1], v[132:133], v[0:1]
	s_waitcnt vmcnt(13)
	v_pk_add_f32 v[120:121], v[138:139], v[204:205]
	v_pk_add_f32 v[2:3], v[136:137], v[2:3]
	s_waitcnt vmcnt(12)
	v_pk_add_f32 v[122:123], v[142:143], v[206:207]
	v_pk_add_f32 v[4:5], v[140:141], v[4:5]
	s_waitcnt vmcnt(11)
	v_cvt_f32_f16_e32 v124, v144
	v_cvt_f32_f16_sdwa v125, v144 dst_sel:DWORD dst_unused:UNUSED_PAD src0_sel:WORD_1
	v_cvt_f32_f16_e32 v126, v145
	v_cvt_f32_f16_sdwa v127, v145 dst_sel:DWORD dst_unused:UNUSED_PAD src0_sel:WORD_1
	v_cvt_f32_f16_e32 v128, v146
	v_cvt_f32_f16_sdwa v129, v146 dst_sel:DWORD dst_unused:UNUSED_PAD src0_sel:WORD_1
	v_cvt_f32_f16_e32 v132, v147
	v_cvt_f32_f16_sdwa v133, v147 dst_sel:DWORD dst_unused:UNUSED_PAD src0_sel:WORD_1
	s_waitcnt vmcnt(10)
	v_cvt_f32_f16_e32 v134, v148
	v_cvt_f32_f16_sdwa v135, v148 dst_sel:DWORD dst_unused:UNUSED_PAD src0_sel:WORD_1
	v_cvt_f32_f16_e32 v136, v149
	v_cvt_f32_f16_sdwa v137, v149 dst_sel:DWORD dst_unused:UNUSED_PAD src0_sel:WORD_1
	v_cvt_f32_f16_e32 v138, v150
	v_cvt_f32_f16_sdwa v139, v150 dst_sel:DWORD dst_unused:UNUSED_PAD src0_sel:WORD_1
	v_cvt_f32_f16_e32 v140, v151
	v_cvt_f32_f16_sdwa v141, v151 dst_sel:DWORD dst_unused:UNUSED_PAD src0_sel:WORD_1
	s_waitcnt vmcnt(9)
	v_cvt_f32_f16_e32 v142, v152
	v_cvt_f32_f16_sdwa v143, v152 dst_sel:DWORD dst_unused:UNUSED_PAD src0_sel:WORD_1
	v_cvt_f32_f16_e32 v144, v153
	v_cvt_f32_f16_sdwa v145, v153 dst_sel:DWORD dst_unused:UNUSED_PAD src0_sel:WORD_1
	v_cvt_f32_f16_e32 v146, v154
	v_cvt_f32_f16_sdwa v147, v154 dst_sel:DWORD dst_unused:UNUSED_PAD src0_sel:WORD_1
	v_cvt_f32_f16_e32 v148, v155
	v_cvt_f32_f16_sdwa v149, v155 dst_sel:DWORD dst_unused:UNUSED_PAD src0_sel:WORD_1
	s_waitcnt vmcnt(8)
	v_cvt_f32_f16_e32 v150, v156
	v_cvt_f32_f16_sdwa v151, v156 dst_sel:DWORD dst_unused:UNUSED_PAD src0_sel:WORD_1
	v_cvt_f32_f16_e32 v152, v157
	v_cvt_f32_f16_sdwa v153, v157 dst_sel:DWORD dst_unused:UNUSED_PAD src0_sel:WORD_1
	v_cvt_f32_f16_e32 v154, v158
	v_cvt_f32_f16_sdwa v155, v158 dst_sel:DWORD dst_unused:UNUSED_PAD src0_sel:WORD_1
	v_cvt_f32_f16_e32 v156, v159
	v_cvt_f32_f16_sdwa v157, v159 dst_sel:DWORD dst_unused:UNUSED_PAD src0_sel:WORD_1
	v_mul_f32_e32 v158, v97, v97
	v_mul_f32_e32 v159, v7, v7
	v_mul_f32_e32 v192, v13, v13
	v_mul_f32_e32 v193, v113, v113
	v_mul_f32_e32 v194, v15, v15
	v_mul_f32_e32 v195, v111, v111
	v_fmac_f32_e32 v158, v96, v96
	v_fmac_f32_e32 v159, v6, v6
	v_fmac_f32_e32 v192, v12, v12
	v_fmac_f32_e32 v193, v112, v112
	v_mul_f32_e32 v196, v9, v9
	v_mul_f32_e32 v197, v115, v115
	v_fmac_f32_e32 v194, v14, v14
	v_fmac_f32_e32 v195, v110, v110
	v_add_f32_e32 v158, v158, v159
	v_add_f32_e32 v159, v192, v193
	v_mul_f32_e32 v198, v11, v11
	v_mul_f32_e32 v199, v117, v117
	v_fmac_f32_e32 v196, v8, v8
	v_fmac_f32_e32 v197, v114, v114
	v_add_f32_e32 v192, v194, v195
	v_add_f32_e32 v158, v158, v159
	v_mul_f32_e32 v200, v1, v1
	v_mul_f32_e32 v201, v119, v119
	v_fmac_f32_e32 v198, v10, v10
	v_fmac_f32_e32 v199, v116, v116
	v_add_f32_e32 v193, v196, v197
	v_add_f32_e32 v158, v158, v192
	v_mul_f32_e32 v202, v3, v3
	v_mul_f32_e32 v203, v121, v121
	v_fmac_f32_e32 v200, v0, v0
	v_fmac_f32_e32 v201, v118, v118
	v_add_f32_e32 v194, v198, v199
	v_add_f32_e32 v158, v193, v158
	v_mul_f32_e32 v204, v5, v5
	v_mul_f32_e32 v205, v123, v123
	v_fmac_f32_e32 v202, v2, v2
	v_fmac_f32_e32 v203, v120, v120
	v_add_f32_e32 v195, v200, v201
	s_waitcnt vmcnt(7)
	v_pk_add_f32 v[126:127], v[162:163], v[126:127]
	v_pk_add_f32 v[124:125], v[160:161], v[124:125]
	v_add_f32_e32 v158, v158, v194
	v_fmac_f32_e32 v204, v4, v4
	v_fmac_f32_e32 v205, v122, v122
	v_add_f32_e32 v196, v202, v203
	s_waitcnt vmcnt(6)
	v_pk_add_f32 v[132:133], v[166:167], v[132:133]
	v_pk_add_f32 v[128:129], v[164:165], v[128:129]
	v_mul_f32_e32 v159, v125, v125
	v_mul_f32_e32 v160, v127, v127
	v_add_f32_e32 v158, v195, v158
	v_add_f32_e32 v197, v204, v205
	s_waitcnt vmcnt(5)
	v_pk_add_f32 v[136:137], v[170:171], v[136:137]
	v_pk_add_f32 v[134:135], v[168:169], v[134:135]
	v_mul_f32_e32 v161, v129, v129
	v_mul_f32_e32 v162, v133, v133
	v_fmac_f32_e32 v159, v124, v124
	v_fmac_f32_e32 v160, v126, v126
	v_add_f32_e32 v158, v158, v196
	s_waitcnt vmcnt(4)
	v_pk_add_f32 v[140:141], v[174:175], v[140:141]
	v_pk_add_f32 v[138:139], v[172:173], v[138:139]
	v_mul_f32_e32 v163, v135, v135
	v_mul_f32_e32 v164, v137, v137
	v_fmac_f32_e32 v161, v128, v128
	v_fmac_f32_e32 v162, v132, v132
	v_add_f32_e32 v159, v159, v160
	v_add_f32_e32 v158, v197, v158
	s_waitcnt vmcnt(3)
	v_pk_add_f32 v[144:145], v[178:179], v[144:145]
	v_pk_add_f32 v[142:143], v[176:177], v[142:143]
	v_mul_f32_e32 v165, v139, v139
	v_mul_f32_e32 v166, v141, v141
	v_fmac_f32_e32 v163, v134, v134
	v_fmac_f32_e32 v164, v136, v136
	v_add_f32_e32 v160, v161, v162
	v_add_f32_e32 v158, v158, v159
	s_waitcnt vmcnt(2)
	v_pk_add_f32 v[148:149], v[182:183], v[148:149]
	v_pk_add_f32 v[146:147], v[180:181], v[146:147]
	v_mul_f32_e32 v167, v143, v143
	v_mul_f32_e32 v168, v145, v145
	v_fmac_f32_e32 v165, v138, v138
	v_fmac_f32_e32 v166, v140, v140
	v_add_f32_e32 v161, v163, v164
	v_add_f32_e32 v158, v160, v158
	s_waitcnt vmcnt(1)
	v_pk_add_f32 v[152:153], v[186:187], v[152:153]
	v_pk_add_f32 v[150:151], v[184:185], v[150:151]
	v_mul_f32_e32 v169, v147, v147
	v_mul_f32_e32 v170, v149, v149
	v_fmac_f32_e32 v167, v142, v142
	v_fmac_f32_e32 v168, v144, v144
	v_add_f32_e32 v162, v165, v166
	v_add_f32_e32 v158, v158, v161
	s_waitcnt vmcnt(0)
	s_cbranch_scc0 .Lp5_notouch
	v_readfirstlane_b32 s0, v94
	v_readfirstlane_b32 s1, v95
	v_lshlrev_b32_e32 v209, 2, v130
	v_add_u32_e32 v210, 0x2000, v209
	global_load_dword v211, v209, s[8:9]
	global_load_dword v212, v210, s[8:9]
	s_nop 1
	global_load_dword v213, v209, s[0:1]
; #define GAS __attribute__((address_space(1)))
; template <bool SAMPLE, bool PRE = false> __device__ __forceinline__ void p5_row(Frame& F, int m, float* dst, const f32x4* xpre = nullptr) {
;     ...
;     float s = 0.f;
; #pragma unroll
;     for (int j = 0; j < 16; ++j) s += (v[j].x * v[j].x + v[j].y * v[j].y) + (v[j].z * v[j].z + v[j].w * v[j].w);
;     const float rstd = 1.0f / sqrtf(wave_sum(s) * (1.0f / DM) + EPS);
;     const GAS f32x4* g8 = (const GAS f32x4*)F.in[20] + 2 * F.lane; GAS f32x4* y8 = (GAS f32x4*)(dst + (size_t)m * DM) + 2 * F.lane;
;     f32x4 gv[16];
; #pragma unroll
;     for (int j = 0; j < 8; ++j) { gv[2 * j] = g8[128 * j]; gv[2 * j + 1] = g8[128 * j + 1]; }
; #pragma unroll
;     for (int j = 0; j < 8; ++j) { y8[128 * j] = v[2 * j] * rstd * gv[2 * j]; y8[128 * j + 1] = v[2 * j + 1] * rstd * gv[2 * j + 1]; }
; }
; __device__ __forceinline__ void p5_final_norm(Frame& F, float* dst, const f32x4 (&xpre)[16]) {
;     const int gw = F.vcu * NWAVES + F.wave, NGW = F.G * NWAVES;
;     for (int r = F.wave * F.G + F.vcu; r < MS; r += NGW) p5_row<true>(F, MP + r, dst);
;     if (gw < MP) p5_row<false, true>(F, gw, dst, xpre);
;     for (int m = gw + NGW; m < MP; m += NGW) p5_row<false>(F, m, dst);
.Lp5_notouch:
	v_pk_add_f32 v[156:157], v[190:191], v[156:157]
	v_pk_add_f32 v[154:155], v[188:189], v[154:155]
	v_mul_f32_e32 v171, v151, v151
	v_mul_f32_e32 v172, v153, v153
	v_fmac_f32_e32 v169, v146, v146
	v_fmac_f32_e32 v170, v148, v148
	v_add_f32_e32 v163, v167, v168
	v_add_f32_e32 v158, v162, v158
	v_mul_f32_e32 v173, v155, v155
	v_mul_f32_e32 v174, v157, v157
	v_fmac_f32_e32 v171, v150, v150
	v_fmac_f32_e32 v172, v152, v152
	v_add_f32_e32 v164, v169, v170
	v_add_f32_e32 v158, v158, v163
	v_fmac_f32_e32 v173, v154, v154
	v_fmac_f32_e32 v174, v156, v156
	v_add_f32_e32 v165, v171, v172
	v_add_f32_e32 v158, v164, v158
	v_add_f32_e32 v166, v173, v174
	v_add_f32_e32 v158, v158, v165
	v_add_f32_e32 v158, v166, v158
	s_nop 1
	v_add_f32_dpp v158, v158, v158 quad_perm:[1,0,3,2] row_mask:0xf bank_mask:0xf bound_ctrl:1
	s_nop 1
	v_add_f32_dpp v158, v158, v158 quad_perm:[2,3,0,1] row_mask:0xf bank_mask:0xf bound_ctrl:1
	s_nop 1
	v_add_f32_dpp v158, v158, v158 row_half_mirror row_mask:0xf bank_mask:0xf bound_ctrl:1
	s_nop 1
	v_add_f32_dpp v158, v158, v158 row_mirror row_mask:0xf bank_mask:0xf bound_ctrl:1
	s_nop 1
	v_mov_b32_dpp v109, v158 row_bcast:15 row_mask:0xa bank_mask:0xf
	v_add_f32_e32 v109, v158, v109
	s_nop 1
	v_mov_b32_dpp v208, v109 row_bcast:31 row_mask:0xc bank_mask:0xf
	v_add_f32_e32 v109, v109, v208
	s_nop 0
	v_readlane_b32 s0, v109, 63
	s_nop 1
	v_fma_f32 v109, s0, v107, v106
	v_mul_f32_e32 v158, 0x4f800000, v109
	v_cmp_gt_f32_e32 vcc, s26, v109
	s_nop 1
	v_cndmask_b32_e32 v109, v109, v158, vcc
	v_sqrt_f32_e32 v158, v109
	s_nop 0
	v_add_u32_e32 v159, -1, v158
	v_add_u32_e32 v160, 1, v158
	v_fma_f32 v161, -v159, v158, v109
	v_fma_f32 v162, -v160, v158, v109
	v_cmp_ge_f32_e64 s[0:1], 0, v161
	s_nop 1
	v_cndmask_b32_e64 v158, v158, v159, s[0:1]
	v_cmp_lt_f32_e64 s[0:1], 0, v162
	s_nop 1
	v_cndmask_b32_e64 v158, v158, v160, s[0:1]
	v_mul_f32_e32 v159, 0x37800000, v158
	v_cndmask_b32_e32 v158, v158, v159, vcc
	v_cmp_class_f32_e32 vcc, v109, v108
	s_nop 1
	v_cndmask_b32_e32 v109, v158, v109, vcc
	v_div_scale_f32 v158, s[0:1], v109, v109, 1.0
	v_rcp_f32_e32 v160, v158
	v_div_scale_f32 v159, vcc, 1.0, v109, 1.0
	v_fma_f32 v161, -v158, v160, 1.0
	v_fmac_f32_e32 v160, v161, v160
	v_mul_f32_e32 v161, v159, v160
	v_fma_f32 v162, -v158, v161, v159
	v_fmac_f32_e32 v161, v162, v160
	v_fma_f32 v158, -v158, v161, v159
	v_div_fmas_f32 v158, v158, v160, v161
	v_div_fixup_f32 v158, v158, v109, 1.0
	v_pk_mul_f32 v[96:97], v[96:97], v[158:159] op_sel_hi:[1,0]
	v_pk_mul_f32 v[6:7], v[6:7], v[158:159] op_sel_hi:[1,0]
	v_pk_mul_f32 v[12:13], v[12:13], v[158:159] op_sel_hi:[1,0]
	v_pk_mul_f32 v[112:113], v[112:113], v[158:159] op_sel_hi:[1,0]
	v_pk_mul_f32 v[14:15], v[14:15], v[158:159] op_sel_hi:[1,0]
	v_pk_mul_f32 v[110:111], v[110:111], v[158:159] op_sel_hi:[1,0]
	v_pk_mul_f32 v[160:161], v[8:9], v[158:159] op_sel_hi:[1,0]
	v_pk_mul_f32 v[114:115], v[114:115], v[158:159] op_sel_hi:[1,0]
	v_pk_mul_f32 v[162:163], v[10:11], v[158:159] op_sel_hi:[1,0]
	v_pk_mul_f32 v[116:117], v[116:117], v[158:159] op_sel_hi:[1,0]
	v_pk_mul_f32 v[164:165], v[0:1], v[158:159] op_sel_hi:[1,0]
	v_pk_mul_f32 v[118:119], v[118:119], v[158:159] op_sel_hi:[1,0]
	v_pk_mul_f32 v[166:167], v[2:3], v[158:159] op_sel_hi:[1,0]
	v_pk_mul_f32 v[120:121], v[120:121], v[158:159] op_sel_hi:[1,0]
	v_pk_mul_f32 v[168:169], v[4:5], v[158:159] op_sel_hi:[1,0]
	v_pk_mul_f32 v[122:123], v[122:123], v[158:159] op_sel_hi:[1,0]
	v_pk_mul_f32 v[124:125], v[124:125], v[158:159] op_sel_hi:[1,0]
	v_pk_mul_f32 v[126:127], v[126:127], v[158:159] op_sel_hi:[1,0]
	v_pk_mul_f32 v[128:129], v[128:129], v[158:159] op_sel_hi:[1,0]
	v_pk_mul_f32 v[132:133], v[132:133], v[158:159] op_sel_hi:[1,0]
	v_pk_mul_f32 v[134:135], v[134:135], v[158:159] op_sel_hi:[1,0]
	v_pk_mul_f32 v[136:137], v[136:137], v[158:159] op_sel_hi:[1,0]
	v_pk_mul_f32 v[138:139], v[138:139], v[158:159] op_sel_hi:[1,0]
	v_pk_mul_f32 v[140:141], v[140:141], v[158:159] op_sel_hi:[1,0]
	v_pk_mul_f32 v[142:143], v[142:143], v[158:159] op_sel_hi:[1,0]
	v_pk_mul_f32 v[144:145], v[144:145], v[158:159] op_sel_hi:[1,0]
	v_pk_mul_f32 v[146:147], v[146:147], v[158:159] op_sel_hi:[1,0]
	v_pk_mul_f32 v[148:149], v[148:149], v[158:159] op_sel_hi:[1,0]
	v_pk_mul_f32 v[150:151], v[150:151], v[158:159] op_sel_hi:[1,0]
	v_pk_mul_f32 v[152:153], v[152:153], v[158:159] op_sel_hi:[1,0]
	v_pk_mul_f32 v[154:155], v[154:155], v[158:159] op_sel_hi:[1,0]
	v_pk_mul_f32 v[156:157], v[156:157], v[158:159] op_sel_hi:[1,0]
	v_pk_mul_f32 v[2:3], v[78:79], v[6:7]
	v_pk_mul_f32 v[0:1], v[76:77], v[96:97]
	v_pk_mul_f32 v[6:7], v[70:71], v[112:113]
	v_pk_mul_f32 v[4:5], v[68:69], v[12:13]
	v_pk_mul_f32 v[10:11], v[74:75], v[110:111]
	v_pk_mul_f32 v[8:9], v[72:73], v[14:15]
	v_pk_mul_f32 v[14:15], v[62:63], v[114:115]
	v_pk_mul_f32 v[12:13], v[60:61], v[160:161]
	v_pk_mul_f32 v[62:63], v[66:67], v[116:117]
	v_pk_mul_f32 v[60:61], v[64:65], v[162:163]
	v_pk_mul_f32 v[54:55], v[54:55], v[118:119]
	v_pk_mul_f32 v[52:53], v[52:53], v[164:165]
	v_pk_mul_f32 v[58:59], v[120:121], v[58:59]
	v_pk_mul_f32 v[56:57], v[166:167], v[56:57]
	v_pk_mul_f32 v[46:47], v[122:123], v[46:47]
	v_pk_mul_f32 v[44:45], v[168:169], v[44:45]
	v_pk_mul_f32 v[50:51], v[126:127], v[50:51]
	v_pk_mul_f32 v[48:49], v[124:125], v[48:49]
	v_pk_mul_f32 v[38:39], v[132:133], v[38:39]
	v_pk_mul_f32 v[36:37], v[128:129], v[36:37]
	v_pk_mul_f32 v[42:43], v[136:137], v[42:43]
	v_pk_mul_f32 v[40:41], v[134:135], v[40:41]
	v_pk_mul_f32 v[30:31], v[140:141], v[30:31]
	v_pk_mul_f32 v[28:29], v[138:139], v[28:29]
	v_pk_mul_f32 v[34:35], v[144:145], v[34:35]
	v_pk_mul_f32 v[32:33], v[142:143], v[32:33]
	v_pk_mul_f32 v[22:23], v[148:149], v[22:23]
	v_pk_mul_f32 v[20:21], v[146:147], v[20:21]
	v_pk_mul_f32 v[26:27], v[152:153], v[26:27]
	v_pk_mul_f32 v[24:25], v[150:151], v[24:25]
	v_pk_mul_f32 v[18:19], v[156:157], v[18:19]
	v_pk_mul_f32 v[16:17], v[154:155], v[16:17]
	global_store_dwordx4 v[98:99], v[0:3], off
	global_store_dwordx4 v[98:99], v[4:7], off offset:16
	global_store_dwordx4 v[98:99], v[8:11], off offset:2048
	global_store_dwordx4 v[98:99], v[12:15], off offset:2064
	global_store_dwordx4 v[102:103], v[60:63], off offset:-4096
	global_store_dwordx4 v[104:105], v[52:55], off offset:16
	global_store_dwordx4 v[104:105], v[56:59], off offset:2048
	global_store_dwordx4 v[104:105], v[44:47], off offset:2064
	global_store_dwordx4 v[102:103], v[48:51], off
	global_store_dwordx4 v[102:103], v[36:39], off offset:16
	global_store_dwordx4 v[102:103], v[40:43], off offset:2048
	global_store_dwordx4 v[102:103], v[28:31], off offset:2064
	global_store_dwordx4 v[100:101], v[32:35], off
	global_store_dwordx4 v[100:101], v[20:23], off offset:16
	global_store_dwordx4 v[100:101], v[24:27], off offset:2048
	global_store_dwordx4 v[100:101], v[16:19], off offset:2064
	s_cbranch_scc1 .LBB0_842
